# attention scale block: in-place softmax scale FMAs packed as v_pk_fma_f32 in the VALU-only zone (diff and GQA loops)
# speedup vs baseline: 1.0051x; 1.0051x over previous
; __device__ __forceinline__ void partialSM(f32x16& p0, f32x16& p1, float& m_reg, float& mn, float& alpha, float C, float thrRaw) {
;     ...
;   float mnC = -mn * C;
; #pragma unroll
;   for (int r = 0; r < 16; ++r) p0[r] = fmaf(p0[r], C, mnC);
; #pragma unroll
;   for (int r = 0; r < 16; ++r) p1[r] = fmaf(p1[r], C, mnC);
; #pragma unroll
;   for (int r = 0; r < 16; ++r) p0[r] = __builtin_amdgcn_exp2f(p0[r]);
.LBB0_664:
	v_cndmask_b32_e64 v215, v130, v134, s[2:3]
	v_mul_f32_e32 v216, 0xbe0293ee, v215
	s_mov_b32 s2, 0x3e0293ee
	v_pk_fma_f32 v[82:83], v[82:83], s[2:3], v[216:217] op_sel_hi:[1,0,0]
	v_pk_fma_f32 v[84:85], v[84:85], s[2:3], v[216:217] op_sel_hi:[1,0,0]
	v_pk_fma_f32 v[86:87], v[86:87], s[2:3], v[216:217] op_sel_hi:[1,0,0]
	v_pk_fma_f32 v[88:89], v[88:89], s[2:3], v[216:217] op_sel_hi:[1,0,0]
	v_pk_fma_f32 v[90:91], v[90:91], s[2:3], v[216:217] op_sel_hi:[1,0,0]
	v_pk_fma_f32 v[92:93], v[92:93], s[2:3], v[216:217] op_sel_hi:[1,0,0]
	v_pk_fma_f32 v[94:95], v[94:95], s[2:3], v[216:217] op_sel_hi:[1,0,0]
	v_pk_fma_f32 v[96:97], v[96:97], s[2:3], v[216:217] op_sel_hi:[1,0,0]
	v_exp_f32_e32 v130, v82
	v_exp_f32_e32 v145, v83
	v_exp_f32_e32 v131, v84
	v_exp_f32_e32 v144, v85
	v_exp_f32_e32 v132, v86
	v_exp_f32_e32 v143, v87
	v_exp_f32_e32 v133, v88
	v_exp_f32_e32 v142, v89
	v_exp_f32_e32 v134, v90
	v_exp_f32_e32 v141, v91
	v_exp_f32_e32 v135, v92
	v_exp_f32_e32 v140, v93
	v_exp_f32_e32 v136, v94
	v_exp_f32_e32 v139, v95
	v_exp_f32_e32 v137, v96
	v_exp_f32_e32 v138, v97
	v_fmamk_f32 v218, v71, 0x3e0293ee, v216
	v_fmamk_f32 v217, v78, 0x3e0293ee, v216
	s_add_i32 s8, s8, 2
	v_fmamk_f32 v225, v66, 0x3e0293ee, v216
	v_fmamk_f32 v226, v67, 0x3e0293ee, v216
	v_fmamk_f32 v227, v68, 0x3e0293ee, v216
	v_fmamk_f32 v228, v69, 0x3e0293ee, v216
	v_fmamk_f32 v229, v70, 0x3e0293ee, v216
	v_fmamk_f32 v219, v72, 0x3e0293ee, v216
	v_fmamk_f32 v220, v73, 0x3e0293ee, v216
	v_fmamk_f32 v221, v74, 0x3e0293ee, v216
	v_fmamk_f32 v222, v75, 0x3e0293ee, v216
	v_fmamk_f32 v223, v76, 0x3e0293ee, v216
	v_fmamk_f32 v224, v77, 0x3e0293ee, v216
	v_fmamk_f32 v230, v79, 0x3e0293ee, v216
	v_fmamk_f32 v231, v80, 0x3e0293ee, v216
	v_fmac_f32_e32 v216, 0x3e0293ee, v81
	s_waitcnt lgkmcnt(0)
	s_barrier
; #define SBAR() __builtin_amdgcn_sched_barrier(0)
; #define SLOAD(i, k0) do { sr_[i].vs0 = *reinterpret_cast<const bf16x8*>(&Vh[(long)((k0) + sr) * LDP + sc]); sr_[i].vs1 = *reinterpret_cast<const bf16x8*>(&Vh[(long)((k0) + 32 + sr) * LDP + sc]); \
;     sr_[i].ks0 = *reinterpret_cast<const bf16x8*>(&Kh[(long)((k0) + ksr) * LDP + ksc]); if (DK == 128) sr_[i].ks1 = *reinterpret_cast<const bf16x8*>(&Kh[(long)((k0) + 32 + ksr) * LDP + ksc]); } while (0)
; #define HOOK(P0, P1, j) do { if (NA) na_hook(P0, P1, krow0 + (j), q_row, q_col, win_r, win_c, rpb, inv_scale, hi); } while (0)
; __device__ __forceinline__ void finishSM(f32x16& p0, f32x16& p1, float alpha, float& l_reg, bf16x8& pa0, bf16x8& pa1, bf16x8& pa2, bf16x8& pa3) {
; #pragma unroll
;   for (int r = 0; r < 16; ++r) p1[r] = __builtin_amdgcn_exp2f(p1[r]);
;   float ps = 0;
; #pragma unroll
;   for (int r = 0; r < 16; ++r) ps += p0[r];
; #pragma unroll
;   for (int r = 0; r < 16; ++r) ps += p1[r];
;   { auto rr = __builtin_amdgcn_permlane32_swap(__float_as_uint(ps), __float_as_uint(ps), false, false);
;     ps = __uint_as_float(rr[0]) + __uint_as_float(rr[1]); }
;   l_reg = l_reg * alpha + ps;
;     ...
;   PK4(p0, 0, pa0); PK4(p0, 8, pa1); PK4(p1, 0, pa2); PK4(p1, 8, pa3);
;     ...
; }
; template <int DK, bool QL>
; __device__ __forceinline__ void qkt(f32x16& p0, f32x16& p1, const bf16* Ks, const bf16x8* qr, const char* ql, int r32, int hi) {
;   p0 = f32x16{}; p1 = f32x16{};
; #pragma unroll
;   for (int d0 = 0; d0 < DK / 16; ++d0) { int cb = (d0 * 16 + hi * 8) * 2;
;     const bf16x8 qv = QL ? *reinterpret_cast<const bf16x8*>(ql + d0 * 1024) : qr[d0];
;     bf16x8 b0 = *reinterpret_cast<const bf16x8*>((const char*)Ks + kswz<DK>(r32, cb));
;     bf16x8 b1 = *reinterpret_cast<const bf16x8*>((const char*)Ks + kswz<DK>(32 + r32, cb));
;     p0 = __builtin_amdgcn_mfma_f32_32x32x16_bf16(b0, qv, p0, 0, 0, 0);
;     p1 = __builtin_amdgcn_mfma_f32_32x32x16_bf16(b1, qv, p1, 0, 0, 0); }
; template <int DK, bool NA, bool QL, int SD> ...
;     ...
;     SBAR(); qkt<DK, QL>(pA0, pA1, K_lds, qr, ql, r32, hi); HOOK(pA0, pA1, j + 1);
;     finishSM(pB0, pB1, alB, l_reg, pa0, pa1, pa2, pa3); SBAR();
;     if (SD == 1 || j + 3 < NT) SLOAD(SE, (j + 1 + SD) * KVBLK); SBAR();
	ds_write_b128 v209, v[106:109]
	ds_write_b128 v210, v[110:113]
	ds_read_b128 v[66:69], v153
	ds_read_b128 v[70:73], v159 offset:32768
	ds_read_b128 v[74:77], v159 offset:40960
	ds_read_b128 v[232:235], v153 offset:1024
	ds_read_b128 v[236:239], v207 offset:32768
	ds_read_b128 v[240:243], v207 offset:40960
	v_exp_f32_e32 v174, v219
	v_exp_f32_e32 v219, v221
	s_waitcnt lgkmcnt(4)
	v_mfma_f32_32x32x16_bf16 v[82:97], v[70:73], v[66:69], 0
	v_exp_f32_e32 v221, v223
	v_exp_f32_e32 v223, v217
	v_add_f32_e32 v217, v145, v130
	v_add_f32_e32 v217, v131, v217
	v_add_f32_e32 v217, v144, v217
	v_add_f32_e32 v217, v132, v217
	s_waitcnt lgkmcnt(3)
	v_mfma_f32_32x32x16_bf16 v[66:81], v[74:77], v[66:69], 0
	v_add_f32_e32 v217, v143, v217
	v_add_f32_e32 v217, v133, v217
	v_add_f32_e32 v217, v142, v217
	v_add_f32_e32 v217, v134, v217
	v_add_f32_e32 v217, v141, v217
	v_add_f32_e32 v217, v135, v217
	v_add_f32_e32 v217, v140, v217
	s_waitcnt lgkmcnt(1)
	v_mfma_f32_32x32x16_bf16 v[82:97], v[236:239], v[232:235], v[82:97]
	v_exp_f32_e32 v164, v225
	v_add_f32_e32 v217, v136, v217
	v_exp_f32_e32 v165, v226
	v_add_f32_e32 v217, v139, v217
	v_exp_f32_e32 v166, v227
	v_add_f32_e32 v217, v137, v217
	v_exp_f32_e32 v167, v228
	s_waitcnt lgkmcnt(0)
	v_mfma_f32_32x32x16_bf16 v[66:81], v[240:243], v[232:235], v[66:81]
	ds_read_b128 v[232:235], v153 offset:2048
	ds_read_b128 v[236:239], v161 offset:32768
	ds_read_b128 v[240:243], v161 offset:40960
	v_add_f32_e32 v217, v138, v217
	v_exp_f32_e32 v172, v229
	v_add_f32_e32 v217, v164, v217
	v_exp_f32_e32 v173, v218
	v_add_f32_e32 v217, v165, v217
	v_add_f32_e32 v217, v166, v217
	s_waitcnt lgkmcnt(1)
	v_mfma_f32_32x32x16_bf16 v[82:97], v[236:239], v[232:235], v[82:97]
	v_exp_f32_e32 v175, v220
	v_add_f32_e32 v217, v167, v217
	v_add_f32_e32 v217, v172, v217
	v_exp_f32_e32 v220, v222
	v_add_f32_e32 v217, v173, v217
	v_add_f32_e32 v217, v174, v217
	v_exp_f32_e32 v222, v224
	s_waitcnt lgkmcnt(0)
	v_mfma_f32_32x32x16_bf16 v[66:81], v[240:243], v[232:235], v[66:81]
	ds_read_b128 v[232:235], v153 offset:3072
	ds_read_b128 v[236:239], v160 offset:32768
	ds_read_b128 v[240:243], v160 offset:40960
	v_add_f32_e32 v217, v175, v217
	v_add_f32_e32 v217, v219, v217
	v_exp_f32_e32 v224, v230
	v_add_f32_e32 v217, v220, v217
	v_exp_f32_e32 v225, v231
	v_add_f32_e32 v217, v221, v217
	s_waitcnt lgkmcnt(1)
	v_mfma_f32_32x32x16_bf16 v[82:97], v[236:239], v[232:235], v[82:97]
	v_exp_f32_e32 v216, v216
	v_add_f32_e32 v217, v222, v217
	v_add_f32_e32 v217, v223, v217
	v_add_f32_e32 v217, v224, v217
	v_add_f32_e32 v217, v225, v217
	v_add_f32_e32 v217, v216, v217
	v_mov_b32_e32 v218, v217
	s_waitcnt lgkmcnt(0)
	v_mfma_f32_32x32x16_bf16 v[66:81], v[240:243], v[232:235], v[66:81]
	ds_read_b128 v[232:235], v153 offset:4096
	ds_read_b128 v[236:239], v158 offset:32768
	ds_read_b128 v[240:243], v158 offset:40960
	v_permlane32_swap_b32_e32 v217, v218
	s_waitcnt lgkmcnt(1)
	v_mfma_f32_32x32x16_bf16 v[82:97], v[236:239], v[232:235], v[82:97]
	s_waitcnt lgkmcnt(0)
	v_mfma_f32_32x32x16_bf16 v[66:81], v[240:243], v[232:235], v[66:81]
	ds_read_b128 v[232:235], v153 offset:5120
	ds_read_b128 v[236:239], v156 offset:32768
	ds_read_b128 v[240:243], v156 offset:40960
	s_waitcnt lgkmcnt(1)
	v_mfma_f32_32x32x16_bf16 v[82:97], v[236:239], v[232:235], v[82:97]
	s_waitcnt lgkmcnt(0)
	v_mfma_f32_32x32x16_bf16 v[66:81], v[240:243], v[232:235], v[66:81]
	ds_read_b128 v[232:235], v153 offset:6144
	ds_read_b128 v[236:239], v157 offset:32768
	ds_read_b128 v[240:243], v157 offset:40960
	s_waitcnt lgkmcnt(1)
	v_mfma_f32_32x32x16_bf16 v[82:97], v[236:239], v[232:235], v[82:97]
	s_waitcnt lgkmcnt(0)
	v_mfma_f32_32x32x16_bf16 v[66:81], v[240:243], v[232:235], v[66:81]
	ds_read_b128 v[232:235], v153 offset:7168
	ds_read_b128 v[236:239], v176 offset:32768
	ds_read_b128 v[240:243], v176 offset:40960
	v_cvt_pk_bf16_f32 v130, v130, v145
	v_cvt_pk_bf16_f32 v131, v131, v144
	v_cvt_pk_bf16_f32 v132, v132, v143
	v_cvt_pk_bf16_f32 v133, v133, v142
	v_cvt_pk_bf16_f32 v134, v134, v141
	v_cvt_pk_bf16_f32 v135, v135, v140
	s_waitcnt lgkmcnt(1)
	v_mfma_f32_32x32x16_bf16 v[82:97], v[236:239], v[232:235], v[82:97]
	v_cvt_pk_bf16_f32 v136, v136, v139
	v_cvt_pk_bf16_f32 v137, v137, v138
	v_cvt_pk_bf16_f32 v138, v164, v165
	v_cvt_pk_bf16_f32 v139, v166, v167
	v_cvt_pk_bf16_f32 v140, v172, v173
	v_cvt_pk_bf16_f32 v141, v174, v175
	v_cvt_pk_bf16_f32 v142, v219, v220
	s_waitcnt lgkmcnt(0)
	v_mfma_f32_32x32x16_bf16 v[66:81], v[240:243], v[232:235], v[66:81]
	v_cvt_pk_bf16_f32 v143, v221, v222
	v_cvt_pk_bf16_f32 v144, v223, v224
	v_cvt_pk_bf16_f32 v145, v225, v216
	v_permlane32_swap_b32_e32 v130, v132
	v_permlane32_swap_b32_e32 v131, v133
	v_permlane32_swap_b32_e32 v134, v136
	v_permlane32_swap_b32_e32 v135, v137
	v_permlane32_swap_b32_e32 v138, v140
	v_permlane32_swap_b32_e32 v139, v141
	v_permlane32_swap_b32_e32 v142, v144
	v_permlane32_swap_b32_e32 v143, v145
	s_cmp_gt_u32 s8, 60
	s_cselect_b64 s[4:5], -1, 0
	s_and_b64 vcc, exec, s[4:5]
	s_cbranch_vccnz .Lod_gqa
	v_add_co_u32_e32 v98, vcc, 0xfffb0000, v146
	s_nop 1
	v_addc_co_u32_e32 v99, vcc, -1, v147, vcc
	global_load_dwordx4 v[106:109], v[98:99], off
	s_nop 0
	global_load_dwordx4 v[98:101], v[98:99], off offset:-512
	s_nop 0
	global_load_dwordx4 v[110:113], v[146:147], off
	global_load_dwordx4 v[102:105], v[146:147], off offset:-512

; __device__ __forceinline__ void partialSM(f32x16& p0, f32x16& p1, float& m_reg, float& mn, float& alpha, float C, float thrRaw) {
;     ...
;   float mnC = -mn * C;
; #pragma unroll
;   for (int r = 0; r < 16; ++r) p0[r] = fmaf(p0[r], C, mnC);
; #pragma unroll
;   for (int r = 0; r < 16; ++r) p1[r] = fmaf(p1[r], C, mnC);
; #pragma unroll
;   for (int r = 0; r < 16; ++r) p0[r] = __builtin_amdgcn_exp2f(p0[r]);
; }
; __device__ __forceinline__ void finishSM(f32x16& p0, f32x16& p1, float alpha, float& l_reg, bf16x8& pa0, bf16x8& pa1, bf16x8& pa2, bf16x8& pa3) {
; #pragma unroll
;   for (int r = 0; r < 16; ++r) p1[r] = __builtin_amdgcn_exp2f(p1[r]);
;   float ps = 0;
; #pragma unroll
;   for (int r = 0; r < 16; ++r) ps += p0[r];
; #pragma unroll
;   for (int r = 0; r < 16; ++r) ps += p1[r];
;   { auto rr = __builtin_amdgcn_permlane32_swap(__float_as_uint(ps), __float_as_uint(ps), false, false);
;     ps = __uint_as_float(rr[0]) + __uint_as_float(rr[1]); }
;   l_reg = l_reg * alpha + ps;
.LBB0_670:
	v_cndmask_b32_e64 v134, v131, v215, s[2:3]
	v_mul_f32_e32 v120, 0xbe0293ee, v134
	v_mov_b32_e32 v121, v120
	s_mov_b32 s2, 0x3e0293ee
	v_pk_fma_f32 v[82:83], v[82:83], s[2:3], v[120:121] op_sel_hi:[1,0,0]
	v_pk_fma_f32 v[84:85], v[84:85], s[2:3], v[120:121] op_sel_hi:[1,0,0]
	v_pk_fma_f32 v[86:87], v[86:87], s[2:3], v[120:121] op_sel_hi:[1,0,0]
	v_pk_fma_f32 v[88:89], v[88:89], s[2:3], v[120:121] op_sel_hi:[1,0,0]
	v_pk_fma_f32 v[90:91], v[90:91], s[2:3], v[120:121] op_sel_hi:[1,0,0]
	v_pk_fma_f32 v[92:93], v[92:93], s[2:3], v[120:121] op_sel_hi:[1,0,0]
	v_pk_fma_f32 v[94:95], v[94:95], s[2:3], v[120:121] op_sel_hi:[1,0,0]
	v_fmamk_f32 v96, v96, 0x3e0293ee, v120
	v_fmac_f32_e32 v121, 0x3e0293ee, v97
	s_mov_b32 s2, 0x3e0293ee
	v_exp_f32_e32 v145, v82
	v_exp_f32_e32 v216, v83
	v_exp_f32_e32 v131, v84
	v_exp_f32_e32 v215, v85
	v_exp_f32_e32 v132, v86
	v_exp_f32_e32 v144, v87
	v_exp_f32_e32 v133, v88
	v_exp_f32_e32 v143, v89
	v_exp_f32_e32 v140, v90
	v_exp_f32_e32 v142, v91
	v_exp_f32_e32 v139, v92
	v_exp_f32_e32 v141, v93
	v_exp_f32_e32 v136, v94
	v_exp_f32_e32 v138, v95
	v_exp_f32_e32 v135, v96
	v_exp_f32_e32 v137, v121
	v_pk_fma_f32 v[126:127], v[66:67], s[2:3], v[120:121] op_sel_hi:[1,0,0]
	v_add_f32_e32 v66, v212, v213
	v_pk_fma_f32 v[124:125], v[68:69], s[2:3], v[120:121] op_sel_hi:[1,0,0]
	v_pk_fma_f32 v[118:119], v[70:71], s[2:3], v[120:121] op_sel_hi:[1,0,0]
	v_pk_fma_f32 v[116:117], v[72:73], s[2:3], v[120:121] op_sel_hi:[1,0,0]
	v_pk_fma_f32 v[114:115], v[74:75], s[2:3], v[120:121] op_sel_hi:[1,0,0]
	v_pk_fma_f32 v[128:129], v[76:77], s[2:3], v[120:121] op_sel_hi:[1,0,0]
	v_pk_fma_f32 v[122:123], v[78:79], s[2:3], v[120:121] op_sel_hi:[1,0,0]
	v_pk_fma_f32 v[120:121], v[80:81], s[2:3], v[120:121] op_sel_hi:[1,0,0]
	v_fmac_f32_e32 v66, v211, v150
	v_add_f32_e32 v150, v217, v218
	s_mov_b64 s[2:3], 0x140000
	v_fmac_f32_e32 v150, v66, v214
	v_lshl_add_u64 v[146:147], v[146:147], 0, s[2:3]
	s_and_b64 vcc, exec, s[4:5]
	s_waitcnt lgkmcnt(0)
	s_barrier
	s_cbranch_vccnz .LBB0_672
	v_mov_b32_e32 v211, v130
	ds_write_b128 v209, v[244:247] offset:16384
	ds_write_b128 v210, v[194:197] offset:16384
	s_branch .LBB0_660

; __device__ __forceinline__ void partialSM(f32x16& p0, f32x16& p1, float& m_reg, float& mn, float& alpha, float C, float thrRaw) {
;     ...
;   float mnC = -mn * C;
; #pragma unroll
;   for (int r = 0; r < 16; ++r) p0[r] = fmaf(p0[r], C, mnC);
; #pragma unroll
;   for (int r = 0; r < 16; ++r) p1[r] = fmaf(p1[r], C, mnC);
; #pragma unroll
;   for (int r = 0; r < 16; ++r) p0[r] = __builtin_amdgcn_exp2f(p0[r]);
; }
; __device__ __forceinline__ void finishSM(f32x16& p0, f32x16& p1, float alpha, float& l_reg, bf16x8& pa0, bf16x8& pa1, bf16x8& pa2, bf16x8& pa3) {
; #pragma unroll
;   for (int r = 0; r < 16; ++r) p1[r] = __builtin_amdgcn_exp2f(p1[r]);
;   float ps = 0;
; #pragma unroll
;   for (int r = 0; r < 16; ++r) ps += p0[r];
; #pragma unroll
;   for (int r = 0; r < 16; ++r) ps += p1[r];
;   { auto rr = __builtin_amdgcn_permlane32_swap(__float_as_uint(ps), __float_as_uint(ps), false, false);
;     ps = __uint_as_float(rr[0]) + __uint_as_float(rr[1]); }
;   l_reg = l_reg * alpha + ps;
;     ...
;   PK4(p0, 0, pa0); PK4(p0, 8, pa1); PK4(p1, 0, pa2); PK4(p1, 8, pa3);
;     ...
; }
; template <int DK, bool QL>
; __device__ __forceinline__ void qkt(f32x16& p0, f32x16& p1, const bf16* Ks, const bf16x8* qr, const char* ql, int r32, int hi) {
;   p0 = f32x16{}; p1 = f32x16{};
; #pragma unroll
;   for (int d0 = 0; d0 < DK / 16; ++d0) { int cb = (d0 * 16 + hi * 8) * 2;
;     const bf16x8 qv = QL ? *reinterpret_cast<const bf16x8*>(ql + d0 * 1024) : qr[d0];
;     bf16x8 b0 = *reinterpret_cast<const bf16x8*>((const char*)Ks + kswz<DK>(r32, cb));
;     bf16x8 b1 = *reinterpret_cast<const bf16x8*>((const char*)Ks + kswz<DK>(32 + r32, cb));
;     p0 = __builtin_amdgcn_mfma_f32_32x32x16_bf16(b0, qv, p0, 0, 0, 0);
;     p1 = __builtin_amdgcn_mfma_f32_32x32x16_bf16(b1, qv, p1, 0, 0, 0); }
.LBB0_686:
	v_cndmask_b32_e64 v223, v138, v142, s[2:3]
	v_mul_f32_e32 v224, 0xbe38aa3b, v223
	s_mov_b32 s2, 0x3e38aa3b
	v_pk_fma_f32 v[82:83], v[82:83], s[2:3], v[224:225] op_sel_hi:[1,0,0]
	v_pk_fma_f32 v[84:85], v[84:85], s[2:3], v[224:225] op_sel_hi:[1,0,0]
	v_pk_fma_f32 v[86:87], v[86:87], s[2:3], v[224:225] op_sel_hi:[1,0,0]
	v_pk_fma_f32 v[88:89], v[88:89], s[2:3], v[224:225] op_sel_hi:[1,0,0]
	v_pk_fma_f32 v[90:91], v[90:91], s[2:3], v[224:225] op_sel_hi:[1,0,0]
	v_pk_fma_f32 v[92:93], v[92:93], s[2:3], v[224:225] op_sel_hi:[1,0,0]
	v_pk_fma_f32 v[94:95], v[94:95], s[2:3], v[224:225] op_sel_hi:[1,0,0]
	v_pk_fma_f32 v[96:97], v[96:97], s[2:3], v[224:225] op_sel_hi:[1,0,0]
	v_exp_f32_e32 v138, v82
	v_exp_f32_e32 v153, v83
	v_exp_f32_e32 v139, v84
	v_exp_f32_e32 v152, v85
	v_exp_f32_e32 v140, v86
	v_exp_f32_e32 v151, v87
	v_exp_f32_e32 v141, v88
	v_exp_f32_e32 v150, v89
	v_exp_f32_e32 v142, v90
	v_exp_f32_e32 v149, v91
	v_exp_f32_e32 v143, v92
	v_exp_f32_e32 v148, v93
	v_exp_f32_e32 v144, v94
	v_exp_f32_e32 v147, v95
	v_exp_f32_e32 v145, v96
	v_exp_f32_e32 v146, v97
	v_fmamk_f32 v233, v66, 0x3e38aa3b, v224
	v_fmamk_f32 v234, v67, 0x3e38aa3b, v224
	v_fmamk_f32 v235, v68, 0x3e38aa3b, v224
	v_fmamk_f32 v236, v69, 0x3e38aa3b, v224
	v_fmamk_f32 v237, v70, 0x3e38aa3b, v224
	v_fmamk_f32 v226, v71, 0x3e38aa3b, v224
	v_fmamk_f32 v227, v72, 0x3e38aa3b, v224
	v_fmamk_f32 v228, v73, 0x3e38aa3b, v224
	v_fmamk_f32 v229, v74, 0x3e38aa3b, v224
	v_fmamk_f32 v230, v75, 0x3e38aa3b, v224
	v_fmamk_f32 v231, v76, 0x3e38aa3b, v224
	v_fmamk_f32 v232, v77, 0x3e38aa3b, v224
	v_fmamk_f32 v225, v78, 0x3e38aa3b, v224
	v_fmamk_f32 v238, v79, 0x3e38aa3b, v224
	v_fmamk_f32 v239, v80, 0x3e38aa3b, v224
	v_fmac_f32_e32 v224, 0x3e38aa3b, v81
	s_waitcnt lgkmcnt(0)
	s_barrier
	ds_write_b128 v214, v[114:117]
	ds_write_b128 v215, v[118:121]
	ds_read_b128 v[66:69], v212 offset:32768
	ds_read_b128 v[70:73], v212 offset:36864
	v_exp_f32_e32 v164, v233
	v_exp_f32_e32 v233, v224
	v_add_f32_e32 v224, v153, v138
	s_waitcnt lgkmcnt(1)
	v_mfma_f32_32x32x16_bf16 v[82:97], v[66:69], v[110:113], 0
	v_add_f32_e32 v224, v139, v224
	v_add_f32_e32 v224, v152, v224
	v_add_f32_e32 v224, v140, v224
	ds_read_b128 v[240:243], v216 offset:32768
	ds_read_b128 v[244:247], v216 offset:36864
	v_add_f32_e32 v224, v151, v224
	v_add_f32_e32 v224, v141, v224
	v_add_f32_e32 v224, v150, v224
	s_waitcnt lgkmcnt(2)
	v_mfma_f32_32x32x16_bf16 v[66:81], v[70:73], v[110:113], 0
	v_add_f32_e32 v224, v142, v224
	v_add_f32_e32 v224, v149, v224
	v_add_f32_e32 v224, v143, v224
	v_add_f32_e32 v224, v148, v224
	v_add_f32_e32 v224, v144, v224
	v_exp_f32_e32 v165, v234
	v_add_f32_e32 v224, v147, v224
	s_waitcnt lgkmcnt(1)
	v_mfma_f32_32x32x16_bf16 v[82:97], v[240:243], v[106:109], v[82:97]
	v_exp_f32_e32 v166, v235
	v_add_f32_e32 v224, v145, v224
	v_exp_f32_e32 v167, v236
	v_add_f32_e32 v224, v146, v224
	v_exp_f32_e32 v172, v237
	v_add_f32_e32 v224, v164, v224
	v_exp_f32_e32 v173, v226
	s_waitcnt lgkmcnt(0)
	v_mfma_f32_32x32x16_bf16 v[66:81], v[244:247], v[106:109], v[66:81]
	ds_read_b128 v[240:243], v217 offset:32768
	ds_read_b128 v[244:247], v217 offset:36864
	v_add_f32_e32 v224, v165, v224
	v_exp_f32_e32 v174, v227
	v_add_f32_e32 v224, v166, v224
	v_exp_f32_e32 v175, v228
	v_add_f32_e32 v224, v167, v224
	v_exp_f32_e32 v226, v229
	s_waitcnt lgkmcnt(1)
	v_mfma_f32_32x32x16_bf16 v[82:97], v[240:243], v[98:101], v[82:97]
	v_add_f32_e32 v224, v172, v224
	v_exp_f32_e32 v227, v230
	v_add_f32_e32 v224, v173, v224
	v_exp_f32_e32 v228, v231
	v_add_f32_e32 v224, v174, v224
	v_exp_f32_e32 v229, v232
	v_add_f32_e32 v224, v175, v224
	s_waitcnt lgkmcnt(0)
	v_mfma_f32_32x32x16_bf16 v[66:81], v[244:247], v[98:101], v[66:81]
	ds_read_b128 v[240:243], v218 offset:32768
	ds_read_b128 v[244:247], v218 offset:36864
	v_exp_f32_e32 v230, v225
	v_add_f32_e32 v224, v226, v224
	v_exp_f32_e32 v231, v238
	v_add_f32_e32 v224, v227, v224
	v_exp_f32_e32 v232, v239
	v_add_f32_e32 v224, v228, v224
	s_waitcnt lgkmcnt(1)
	v_mfma_f32_32x32x16_bf16 v[82:97], v[240:243], v[102:105], v[82:97]
	v_add_f32_e32 v224, v229, v224
	v_add_f32_e32 v224, v230, v224
	v_add_f32_e32 v224, v231, v224
	v_add_f32_e32 v224, v232, v224
	v_add_f32_e32 v224, v233, v224
	v_mov_b32_e32 v225, v224
	v_cvt_pk_bf16_f32 v138, v138, v153
	s_waitcnt lgkmcnt(0)
	v_mfma_f32_32x32x16_bf16 v[66:81], v[244:247], v[102:105], v[66:81]
	v_cvt_pk_bf16_f32 v139, v139, v152
	v_cvt_pk_bf16_f32 v140, v140, v151
	v_cvt_pk_bf16_f32 v141, v141, v150
	v_cvt_pk_bf16_f32 v142, v142, v149
	v_cvt_pk_bf16_f32 v143, v143, v148
	v_cvt_pk_bf16_f32 v144, v144, v147
	v_cvt_pk_bf16_f32 v145, v145, v146
	v_cvt_pk_bf16_f32 v146, v164, v165
	v_cvt_pk_bf16_f32 v147, v166, v167
	v_cvt_pk_bf16_f32 v148, v172, v173
	v_cvt_pk_bf16_f32 v149, v174, v175
	v_cvt_pk_bf16_f32 v150, v226, v227
	v_cvt_pk_bf16_f32 v151, v228, v229
	v_cvt_pk_bf16_f32 v152, v230, v231
	v_cvt_pk_bf16_f32 v153, v232, v233
	v_permlane32_swap_b32_e32 v224, v225
	v_permlane32_swap_b32_e32 v138, v140
	v_permlane32_swap_b32_e32 v139, v141
	v_permlane32_swap_b32_e32 v142, v144
	v_permlane32_swap_b32_e32 v143, v145
	v_permlane32_swap_b32_e32 v146, v148
	v_permlane32_swap_b32_e32 v147, v149
	v_permlane32_swap_b32_e32 v150, v152
	v_permlane32_swap_b32_e32 v151, v153
	s_cmp_gt_u32 s9, 60
	s_cselect_b64 s[4:5], -1, 0
	s_and_b64 vcc, exec, s[4:5]
	s_cbranch_vccnz .Lod_d1
	global_load_dwordx4 v[114:117], v[178:179], off offset:2048
	global_load_dwordx4 v[118:121], v[180:181], off offset:2048
	global_load_dwordx4 v[122:125], v[204:205], off offset:1024
	s_mov_b32 s6, 0xa0000
	s_mov_b32 s7, 0
	s_nop 0
	v_lshl_add_u64 v[178:179], v[178:179], 0, s[6:7]
	v_lshl_add_u64 v[180:181], v[180:181], 0, s[6:7]
	v_lshl_add_u64 v[204:205], v[204:205], 0, s[6:7]

; __device__ __forceinline__ void partialSM(f32x16& p0, f32x16& p1, float& m_reg, float& mn, float& alpha, float C, float thrRaw) {
;     ...
;   float mnC = -mn * C;
; #pragma unroll
;   for (int r = 0; r < 16; ++r) p0[r] = fmaf(p0[r], C, mnC);
; #pragma unroll
;   for (int r = 0; r < 16; ++r) p1[r] = fmaf(p1[r], C, mnC);
; #pragma unroll
;   for (int r = 0; r < 16; ++r) p0[r] = __builtin_amdgcn_exp2f(p0[r]);
; }
; __device__ __forceinline__ void finishSM(f32x16& p0, f32x16& p1, float alpha, float& l_reg, bf16x8& pa0, bf16x8& pa1, bf16x8& pa2, bf16x8& pa3) {
; #pragma unroll
;   for (int r = 0; r < 16; ++r) p1[r] = __builtin_amdgcn_exp2f(p1[r]);
;   float ps = 0;
; #pragma unroll
;   for (int r = 0; r < 16; ++r) ps += p0[r];
; #pragma unroll
;   for (int r = 0; r < 16; ++r) ps += p1[r];
;   { auto rr = __builtin_amdgcn_permlane32_swap(__float_as_uint(ps), __float_as_uint(ps), false, false);
;     ps = __uint_as_float(rr[0]) + __uint_as_float(rr[1]); }
;   l_reg = l_reg * alpha + ps;
.LBB0_692:
	v_cndmask_b32_e64 v142, v138, v223, s[2:3]
	v_mul_f32_e32 v132, 0xbe38aa3b, v142
	v_mov_b32_e32 v133, v132
	s_mov_b32 s2, 0x3e38aa3b
	v_pk_fma_f32 v[82:83], v[82:83], s[2:3], v[132:133] op_sel_hi:[1,0,0]
	v_pk_fma_f32 v[84:85], v[84:85], s[2:3], v[132:133] op_sel_hi:[1,0,0]
	v_pk_fma_f32 v[86:87], v[86:87], s[2:3], v[132:133] op_sel_hi:[1,0,0]
	v_pk_fma_f32 v[88:89], v[88:89], s[2:3], v[132:133] op_sel_hi:[1,0,0]
	v_pk_fma_f32 v[90:91], v[90:91], s[2:3], v[132:133] op_sel_hi:[1,0,0]
	v_pk_fma_f32 v[92:93], v[92:93], s[2:3], v[132:133] op_sel_hi:[1,0,0]
	v_pk_fma_f32 v[94:95], v[94:95], s[2:3], v[132:133] op_sel_hi:[1,0,0]
	v_fmamk_f32 v96, v96, 0x3e38aa3b, v132
	v_fmac_f32_e32 v133, 0x3e38aa3b, v97
	s_mov_b32 s2, 0x3e38aa3b
	v_exp_f32_e32 v177, v82
	v_exp_f32_e32 v226, v83
	v_exp_f32_e32 v161, v84
	v_exp_f32_e32 v223, v85
	v_exp_f32_e32 v153, v86
	v_exp_f32_e32 v176, v87
	v_exp_f32_e32 v152, v88
	v_exp_f32_e32 v160, v89
	v_exp_f32_e32 v149, v90
	v_exp_f32_e32 v151, v91
	v_exp_f32_e32 v147, v92
	v_exp_f32_e32 v150, v93
	v_exp_f32_e32 v145, v94
	v_exp_f32_e32 v148, v95
	v_exp_f32_e32 v144, v96
	v_exp_f32_e32 v146, v133
	v_pk_fma_f32 v[138:139], v[66:67], s[2:3], v[132:133] op_sel_hi:[1,0,0]
	v_add_f32_e32 v66, v220, v221
	v_pk_fma_f32 v[136:137], v[68:69], s[2:3], v[132:133] op_sel_hi:[1,0,0]
	v_pk_fma_f32 v[130:131], v[70:71], s[2:3], v[132:133] op_sel_hi:[1,0,0]
	v_pk_fma_f32 v[128:129], v[72:73], s[2:3], v[132:133] op_sel_hi:[1,0,0]
	v_pk_fma_f32 v[126:127], v[74:75], s[2:3], v[132:133] op_sel_hi:[1,0,0]
	v_pk_fma_f32 v[140:141], v[76:77], s[2:3], v[132:133] op_sel_hi:[1,0,0]
	v_pk_fma_f32 v[134:135], v[78:79], s[2:3], v[132:133] op_sel_hi:[1,0,0]
	v_pk_fma_f32 v[132:133], v[80:81], s[2:3], v[132:133] op_sel_hi:[1,0,0]
	v_fmac_f32_e32 v66, v219, v209
	v_add_f32_e32 v209, v224, v225
	v_fmac_f32_e32 v209, v66, v222
	s_add_i32 s9, s9, 2
	s_and_b64 vcc, exec, s[4:5]
	s_waitcnt lgkmcnt(0)
	s_barrier
	s_cbranch_vccnz .LBB0_694
	v_mov_b32_e32 v219, v143
	ds_write_b128 v214, v[182:185] offset:16384
	ds_write_b128 v215, v[194:197] offset:16384
	s_branch .LBB0_682

; __device__ __forceinline__ void partialSM(f32x16& p0, f32x16& p1, float& m_reg, float& mn, float& alpha, float C, float thrRaw) {
;     ...
;   float mnC = -mn * C;
; #pragma unroll
;   for (int r = 0; r < 16; ++r) p0[r] = fmaf(p0[r], C, mnC);
; #pragma unroll
;   for (int r = 0; r < 16; ++r) p1[r] = fmaf(p1[r], C, mnC);
; #pragma unroll
;   for (int r = 0; r < 16; ++r) p0[r] = __builtin_amdgcn_exp2f(p0[r]);
; }
; __device__ __forceinline__ void finishSM(f32x16& p0, f32x16& p1, float alpha, float& l_reg, bf16x8& pa0, bf16x8& pa1, bf16x8& pa2, bf16x8& pa3) {
; #pragma unroll
;   for (int r = 0; r < 16; ++r) p1[r] = __builtin_amdgcn_exp2f(p1[r]);
;   float ps = 0;
; #pragma unroll
;   for (int r = 0; r < 16; ++r) ps += p0[r];
; #pragma unroll
;   for (int r = 0; r < 16; ++r) ps += p1[r];
;   { auto rr = __builtin_amdgcn_permlane32_swap(__float_as_uint(ps), __float_as_uint(ps), false, false);
;     ps = __uint_as_float(rr[0]) + __uint_as_float(rr[1]); }
;   l_reg = l_reg * alpha + ps;
;     ...
;   PK4(p0, 0, pa0); PK4(p0, 8, pa1); PK4(p1, 0, pa2); PK4(p1, 8, pa3);
;     ...
; }
; template <int DK, bool QL>
; __device__ __forceinline__ void qkt(f32x16& p0, f32x16& p1, const bf16* Ks, const bf16x8* qr, const char* ql, int r32, int hi) {
;   p0 = f32x16{}; p1 = f32x16{};
; #pragma unroll
;   for (int d0 = 0; d0 < DK / 16; ++d0) { int cb = (d0 * 16 + hi * 8) * 2;
;     const bf16x8 qv = QL ? *reinterpret_cast<const bf16x8*>(ql + d0 * 1024) : qr[d0];
;     bf16x8 b0 = *reinterpret_cast<const bf16x8*>((const char*)Ks + kswz<DK>(r32, cb));
;     bf16x8 b1 = *reinterpret_cast<const bf16x8*>((const char*)Ks + kswz<DK>(32 + r32, cb));
;     p0 = __builtin_amdgcn_mfma_f32_32x32x16_bf16(b0, qv, p0, 0, 0, 0);
;     p1 = __builtin_amdgcn_mfma_f32_32x32x16_bf16(b1, qv, p1, 0, 0, 0); }
.LBB0_705:
	v_cndmask_b32_e64 v223, v138, v142, s[2:3]
	v_mul_f32_e32 v224, 0xbe38aa3b, v223
	s_mov_b32 s2, 0x3e38aa3b
	v_pk_fma_f32 v[82:83], v[82:83], s[2:3], v[224:225] op_sel_hi:[1,0,0]
	v_pk_fma_f32 v[84:85], v[84:85], s[2:3], v[224:225] op_sel_hi:[1,0,0]
	v_pk_fma_f32 v[86:87], v[86:87], s[2:3], v[224:225] op_sel_hi:[1,0,0]
	v_pk_fma_f32 v[88:89], v[88:89], s[2:3], v[224:225] op_sel_hi:[1,0,0]
	v_pk_fma_f32 v[90:91], v[90:91], s[2:3], v[224:225] op_sel_hi:[1,0,0]
	v_pk_fma_f32 v[92:93], v[92:93], s[2:3], v[224:225] op_sel_hi:[1,0,0]
	v_pk_fma_f32 v[94:95], v[94:95], s[2:3], v[224:225] op_sel_hi:[1,0,0]
	v_pk_fma_f32 v[96:97], v[96:97], s[2:3], v[224:225] op_sel_hi:[1,0,0]
	v_exp_f32_e32 v138, v82
	v_exp_f32_e32 v153, v83
	v_exp_f32_e32 v139, v84
	v_exp_f32_e32 v152, v85
	v_exp_f32_e32 v140, v86
	v_exp_f32_e32 v151, v87
	v_exp_f32_e32 v141, v88
	v_exp_f32_e32 v150, v89
	v_exp_f32_e32 v142, v90
	v_exp_f32_e32 v149, v91
	v_exp_f32_e32 v143, v92
	v_exp_f32_e32 v148, v93
	v_exp_f32_e32 v144, v94
	v_exp_f32_e32 v147, v95
	v_exp_f32_e32 v145, v96
	v_exp_f32_e32 v146, v97
	v_fmamk_f32 v233, v66, 0x3e38aa3b, v224
	v_fmamk_f32 v234, v67, 0x3e38aa3b, v224
	v_fmamk_f32 v235, v68, 0x3e38aa3b, v224
	v_fmamk_f32 v236, v69, 0x3e38aa3b, v224
	v_fmamk_f32 v237, v70, 0x3e38aa3b, v224
	v_fmamk_f32 v226, v71, 0x3e38aa3b, v224
	v_fmamk_f32 v227, v72, 0x3e38aa3b, v224
	v_fmamk_f32 v228, v73, 0x3e38aa3b, v224
	v_fmamk_f32 v229, v74, 0x3e38aa3b, v224
	v_fmamk_f32 v230, v75, 0x3e38aa3b, v224
	v_fmamk_f32 v231, v76, 0x3e38aa3b, v224
	v_fmamk_f32 v232, v77, 0x3e38aa3b, v224
	v_fmamk_f32 v225, v78, 0x3e38aa3b, v224
	v_fmamk_f32 v238, v79, 0x3e38aa3b, v224
	v_fmamk_f32 v239, v80, 0x3e38aa3b, v224
	v_fmac_f32_e32 v224, 0x3e38aa3b, v81
	s_waitcnt lgkmcnt(0)
	s_barrier
	ds_write_b128 v212, v[114:117]
	ds_write_b128 v213, v[118:121]
	ds_read_b128 v[66:69], v215 offset:32768
	ds_read_b128 v[70:73], v215 offset:36864
	v_exp_f32_e32 v164, v233
	v_exp_f32_e32 v233, v224
	v_add_f32_e32 v224, v153, v138
	s_waitcnt lgkmcnt(1)
	v_mfma_f32_32x32x16_bf16 v[82:97], v[66:69], v[110:113], 0
	v_add_f32_e32 v224, v139, v224
	v_add_f32_e32 v224, v152, v224
	v_add_f32_e32 v224, v140, v224
	ds_read_b128 v[240:243], v216 offset:32768
	ds_read_b128 v[244:247], v216 offset:36864
	v_add_f32_e32 v224, v151, v224
	v_add_f32_e32 v224, v141, v224
	v_add_f32_e32 v224, v150, v224
	s_waitcnt lgkmcnt(2)
	v_mfma_f32_32x32x16_bf16 v[66:81], v[70:73], v[110:113], 0
	v_add_f32_e32 v224, v142, v224
	v_add_f32_e32 v224, v149, v224
	v_add_f32_e32 v224, v143, v224
	v_add_f32_e32 v224, v148, v224
	v_add_f32_e32 v224, v144, v224
	v_exp_f32_e32 v165, v234
	v_add_f32_e32 v224, v147, v224
	s_waitcnt lgkmcnt(1)
	v_mfma_f32_32x32x16_bf16 v[82:97], v[240:243], v[106:109], v[82:97]
	v_exp_f32_e32 v166, v235
	v_add_f32_e32 v224, v145, v224
	v_exp_f32_e32 v167, v236
	v_add_f32_e32 v224, v146, v224
	v_exp_f32_e32 v172, v237
	v_add_f32_e32 v224, v164, v224
	v_exp_f32_e32 v173, v226
	s_waitcnt lgkmcnt(0)
	v_mfma_f32_32x32x16_bf16 v[66:81], v[244:247], v[106:109], v[66:81]
	ds_read_b128 v[240:243], v217 offset:32768
	ds_read_b128 v[244:247], v217 offset:36864
	v_add_f32_e32 v224, v165, v224
	v_exp_f32_e32 v174, v227
	v_add_f32_e32 v224, v166, v224
	v_exp_f32_e32 v175, v228
	v_add_f32_e32 v224, v167, v224
	v_exp_f32_e32 v226, v229
	s_waitcnt lgkmcnt(1)
	v_mfma_f32_32x32x16_bf16 v[82:97], v[240:243], v[102:105], v[82:97]
	v_add_f32_e32 v224, v172, v224
	v_exp_f32_e32 v227, v230
	v_add_f32_e32 v224, v173, v224
	v_exp_f32_e32 v228, v231
	v_add_f32_e32 v224, v174, v224
	v_exp_f32_e32 v229, v232
	v_add_f32_e32 v224, v175, v224
	s_waitcnt lgkmcnt(0)
	v_mfma_f32_32x32x16_bf16 v[66:81], v[244:247], v[102:105], v[66:81]
	ds_read_b128 v[240:243], v218 offset:32768
	ds_read_b128 v[244:247], v218 offset:36864
	v_exp_f32_e32 v230, v225
	v_add_f32_e32 v224, v226, v224
	v_exp_f32_e32 v231, v238
	v_add_f32_e32 v224, v227, v224
	v_exp_f32_e32 v232, v239
	v_add_f32_e32 v224, v228, v224
	s_waitcnt lgkmcnt(1)
	v_mfma_f32_32x32x16_bf16 v[82:97], v[240:243], v[98:101], v[82:97]
	v_add_f32_e32 v224, v229, v224
	v_add_f32_e32 v224, v230, v224
	v_add_f32_e32 v224, v231, v224
	v_add_f32_e32 v224, v232, v224
	v_add_f32_e32 v224, v233, v224
	v_mov_b32_e32 v225, v224
	v_cvt_pk_bf16_f32 v138, v138, v153
	s_waitcnt lgkmcnt(0)
	v_mfma_f32_32x32x16_bf16 v[66:81], v[244:247], v[98:101], v[66:81]
	v_cvt_pk_bf16_f32 v139, v139, v152
	v_cvt_pk_bf16_f32 v140, v140, v151
	v_cvt_pk_bf16_f32 v141, v141, v150
	v_cvt_pk_bf16_f32 v142, v142, v149
	v_cvt_pk_bf16_f32 v143, v143, v148
	v_cvt_pk_bf16_f32 v144, v144, v147
	v_cvt_pk_bf16_f32 v145, v145, v146
	v_cvt_pk_bf16_f32 v146, v164, v165
	v_cvt_pk_bf16_f32 v147, v166, v167
	v_cvt_pk_bf16_f32 v148, v172, v173
	v_cvt_pk_bf16_f32 v149, v174, v175
	v_cvt_pk_bf16_f32 v150, v226, v227
	v_cvt_pk_bf16_f32 v151, v228, v229
	v_cvt_pk_bf16_f32 v152, v230, v231
	v_cvt_pk_bf16_f32 v153, v232, v233
	v_permlane32_swap_b32_e32 v224, v225
	v_permlane32_swap_b32_e32 v138, v140
	v_permlane32_swap_b32_e32 v139, v141
	v_permlane32_swap_b32_e32 v142, v144
	v_permlane32_swap_b32_e32 v143, v145
	v_permlane32_swap_b32_e32 v146, v148
	v_permlane32_swap_b32_e32 v147, v149
	v_permlane32_swap_b32_e32 v150, v152
	v_permlane32_swap_b32_e32 v151, v153
	s_cmp_gt_u32 s8, 60
	s_cselect_b64 s[4:5], -1, 0
	s_and_b64 vcc, exec, s[4:5]
	s_cbranch_vccnz .Lod_d2
	global_load_dwordx4 v[114:117], v[178:179], off offset:2048
	global_load_dwordx4 v[118:121], v[180:181], off offset:2048
	global_load_dwordx4 v[122:125], v[204:205], off offset:1152
	s_mov_b32 s6, 0xa0000
	s_mov_b32 s7, 0
	s_nop 0
	v_lshl_add_u64 v[178:179], v[178:179], 0, s[6:7]
	v_lshl_add_u64 v[180:181], v[180:181], 0, s[6:7]
	v_lshl_add_u64 v[204:205], v[204:205], 0, s[6:7]

; __device__ __forceinline__ void partialSM(f32x16& p0, f32x16& p1, float& m_reg, float& mn, float& alpha, float C, float thrRaw) {
;     ...
;   float mnC = -mn * C;
; #pragma unroll
;   for (int r = 0; r < 16; ++r) p0[r] = fmaf(p0[r], C, mnC);
; #pragma unroll
;   for (int r = 0; r < 16; ++r) p1[r] = fmaf(p1[r], C, mnC);
; #pragma unroll
;   for (int r = 0; r < 16; ++r) p0[r] = __builtin_amdgcn_exp2f(p0[r]);
; }
; __device__ __forceinline__ void finishSM(f32x16& p0, f32x16& p1, float alpha, float& l_reg, bf16x8& pa0, bf16x8& pa1, bf16x8& pa2, bf16x8& pa3) {
; #pragma unroll
;   for (int r = 0; r < 16; ++r) p1[r] = __builtin_amdgcn_exp2f(p1[r]);
;   float ps = 0;
; #pragma unroll
;   for (int r = 0; r < 16; ++r) ps += p0[r];
; #pragma unroll
;   for (int r = 0; r < 16; ++r) ps += p1[r];
;   { auto rr = __builtin_amdgcn_permlane32_swap(__float_as_uint(ps), __float_as_uint(ps), false, false);
;     ps = __uint_as_float(rr[0]) + __uint_as_float(rr[1]); }
;   l_reg = l_reg * alpha + ps;
.LBB0_711:
	v_cndmask_b32_e64 v142, v138, v223, s[2:3]
	v_mul_f32_e32 v132, 0xbe38aa3b, v142
	v_mov_b32_e32 v133, v132
	s_mov_b32 s2, 0x3e38aa3b
	v_pk_fma_f32 v[82:83], v[82:83], s[2:3], v[132:133] op_sel_hi:[1,0,0]
	v_pk_fma_f32 v[84:85], v[84:85], s[2:3], v[132:133] op_sel_hi:[1,0,0]
	v_pk_fma_f32 v[86:87], v[86:87], s[2:3], v[132:133] op_sel_hi:[1,0,0]
	v_pk_fma_f32 v[88:89], v[88:89], s[2:3], v[132:133] op_sel_hi:[1,0,0]
	v_pk_fma_f32 v[90:91], v[90:91], s[2:3], v[132:133] op_sel_hi:[1,0,0]
	v_pk_fma_f32 v[92:93], v[92:93], s[2:3], v[132:133] op_sel_hi:[1,0,0]
	v_pk_fma_f32 v[94:95], v[94:95], s[2:3], v[132:133] op_sel_hi:[1,0,0]
	v_fmamk_f32 v96, v96, 0x3e38aa3b, v132
	v_fmac_f32_e32 v133, 0x3e38aa3b, v97
	s_mov_b32 s2, 0x3e38aa3b
	v_exp_f32_e32 v177, v82
	v_exp_f32_e32 v226, v83
	v_exp_f32_e32 v161, v84
	v_exp_f32_e32 v223, v85
	v_exp_f32_e32 v153, v86
	v_exp_f32_e32 v176, v87
	v_exp_f32_e32 v152, v88
	v_exp_f32_e32 v160, v89
	v_exp_f32_e32 v149, v90
	v_exp_f32_e32 v151, v91
	v_exp_f32_e32 v147, v92
	v_exp_f32_e32 v150, v93
	v_exp_f32_e32 v145, v94
	v_exp_f32_e32 v148, v95
	v_exp_f32_e32 v144, v96
	v_exp_f32_e32 v146, v133
	v_pk_fma_f32 v[138:139], v[66:67], s[2:3], v[132:133] op_sel_hi:[1,0,0]
	v_add_f32_e32 v66, v220, v221
	v_pk_fma_f32 v[136:137], v[68:69], s[2:3], v[132:133] op_sel_hi:[1,0,0]
	v_pk_fma_f32 v[130:131], v[70:71], s[2:3], v[132:133] op_sel_hi:[1,0,0]
	v_pk_fma_f32 v[128:129], v[72:73], s[2:3], v[132:133] op_sel_hi:[1,0,0]
	v_pk_fma_f32 v[126:127], v[74:75], s[2:3], v[132:133] op_sel_hi:[1,0,0]
	v_pk_fma_f32 v[140:141], v[76:77], s[2:3], v[132:133] op_sel_hi:[1,0,0]
	v_pk_fma_f32 v[134:135], v[78:79], s[2:3], v[132:133] op_sel_hi:[1,0,0]
	v_pk_fma_f32 v[132:133], v[80:81], s[2:3], v[132:133] op_sel_hi:[1,0,0]
	v_fmac_f32_e32 v66, v219, v209
	v_add_f32_e32 v209, v224, v225
	v_fmac_f32_e32 v209, v66, v222
	s_add_i32 s8, s8, 2
	s_and_b64 vcc, exec, s[4:5]
	s_waitcnt lgkmcnt(0)
	s_barrier
	s_cbranch_vccnz .LBB0_713
	v_mov_b32_e32 v219, v143
	ds_write_b128 v212, v[182:185] offset:16384
	ds_write_b128 v213, v[194:197] offset:16384
	s_branch .LBB0_701
